# pool-fold weight-conversion unit: seven dependent load-wait-write steps batched into one load group (both inlined copies)
# baseline (speedup 1.0000x reference)
.LBB0_153:
	s_cmpk_gt_i32 s50, 0x5ff
	s_mov_b64 s[0:1], -1
	s_cbranch_scc0 .LBB0_184
	s_cmpk_gt_u32 s50, 0x6bf
	s_cbranch_scc0 .LBB0_181
	s_cmpk_gt_u32 s50, 0x7bf
	s_cbranch_scc0 .LBB0_178
	s_cmpk_gt_u32 s50, 0xd3f
	s_cbranch_scc0 .LBB0_175
	s_cmpk_gt_u32 s50, 0xfff
	s_cbranch_scc0 .LBB0_172
	s_cmpk_gt_u32 s50, 0x103f
	v_add_u32_e32 v45, 0x1040, v41
	v_add_u32_e32 v46, 0x1048, v41
	v_add_u32_e32 v43, 0x2080, v41
	v_add_u32_e32 v44, 0x2088, v41
	v_add_u32_e32 v36, 0x30c0, v41
	v_add_u32_e32 v37, 0x30c8, v41
	v_lshlrev_b32_e32 v184, 2, v2
	s_cbranch_scc0 .LBB0_164
	s_add_i32 s0, s50, 0xffffefc0
	s_lshr_b32 s88, s0, 4
	s_lshl_b64 s[26:27], s[88:89], 14
	s_lshl_b32 s58, s88, 6
	s_mov_b32 s59, s89
	v_lshl_add_u64 v[34:35], v[30:31], 0, s[26:27]
	v_lshl_add_u64 v[52:53], s[58:59], 2, v[32:33]
	v_lshl_add_u64 v[48:49], v[8:9], 2, v[34:35]
	global_load_dwordx4 v[48:51], v[48:49], off
	s_nop 0
	global_load_dwordx4 v[52:55], v[52:53], off
	s_lshl_b64 s[0:1], s[58:59], 12
	s_add_u32 s33, s29, s0
	s_addc_u32 s1, s54, s1
	s_lshl_b32 s0, s50, 6
	s_and_b32 s0, s0, 0x3c0
	s_lshl_b32 s35, s0, 2
	s_add_u32 s60, s33, s35
	s_addc_u32 s61, s1, 0
	v_lshl_add_u64 v[56:57], s[60:61], 0, v[184:185]
	v_add_u32_e32 v47, 0x4100, v41
	s_mov_b32 s1, 0
	s_lshl_b32 s88, s88, 7
	s_or_b32 s0, s0, 0xc00
	s_mov_b32 s26, s1
	v_lshl_add_u64 v[172:173], v[56:57], 0, v[10:11]
	global_load_dwordx4 v[144:147], v[172:173], off
	v_lshl_add_u64 v[172:173], v[14:15], 2, v[34:35]
	global_load_dwordx4 v[148:151], v[172:173], off
	v_lshl_add_u64 v[172:173], v[56:57], 0, v[16:17]
	global_load_dwordx4 v[152:155], v[172:173], off
	v_lshl_add_u64 v[172:173], v[20:21], 2, v[34:35]
	global_load_dwordx4 v[156:159], v[172:173], off
	v_lshl_add_u64 v[172:173], v[56:57], 0, v[22:23]
	global_load_dwordx4 v[160:163], v[172:173], off
	v_lshl_add_u64 v[172:173], v[26:27], 2, v[34:35]
	global_load_dwordx4 v[164:167], v[172:173], off
	v_lshl_add_u64 v[172:173], v[56:57], 0, v[28:29]
	global_load_dwordx4 v[168:171], v[172:173], off
	s_waitcnt vmcnt(0)
	v_pk_mul_f32 v[48:49], v[48:49], v[52:53]
	ds_write2_b32 v41, v48, v49 offset1:1
	v_pk_mul_f32 v[48:49], v[50:51], v[54:55]
	ds_write2_b32 v41, v48, v49 offset0:2 offset1:3
	v_lshl_add_u64 v[48:49], v[56:57], 0, v[10:11]
	v_mov_b64_e32 v[48:49], v[144:145]
	v_mov_b64_e32 v[50:51], v[146:147]
	s_waitcnt vmcnt(0)
	ds_write2_b32 v47, v48, v49 offset1:1
	v_add_u32_e32 v47, 0x4108, v41
	v_lshl_add_u64 v[48:49], v[14:15], 2, v[34:35]
	ds_write2_b32 v47, v50, v51 offset1:1
	v_mov_b64_e32 v[48:49], v[148:149]
	v_mov_b64_e32 v[50:51], v[150:151]
	v_add_u32_e32 v47, 0x5140, v41
	s_waitcnt vmcnt(0)
	v_pk_mul_f32 v[48:49], v[52:53], v[48:49]
	ds_write2_b32 v45, v48, v49 offset1:1
	v_pk_mul_f32 v[48:49], v[54:55], v[50:51]
	ds_write2_b32 v46, v48, v49 offset1:1
	v_lshl_add_u64 v[48:49], v[56:57], 0, v[16:17]
	v_mov_b64_e32 v[48:49], v[152:153]
	v_mov_b64_e32 v[50:51], v[154:155]
	s_waitcnt vmcnt(0)
	ds_write2_b32 v47, v48, v49 offset1:1
	v_add_u32_e32 v47, 0x5148, v41
	v_lshl_add_u64 v[48:49], v[20:21], 2, v[34:35]
	ds_write2_b32 v47, v50, v51 offset1:1
	v_mov_b64_e32 v[48:49], v[156:157]
	v_mov_b64_e32 v[50:51], v[158:159]
	v_add_u32_e32 v47, 0x6180, v41
	v_lshl_add_u64 v[34:35], v[26:27], 2, v[34:35]
	s_waitcnt vmcnt(0)
	v_pk_mul_f32 v[48:49], v[52:53], v[48:49]
	ds_write2_b32 v43, v48, v49 offset1:1
	v_pk_mul_f32 v[48:49], v[54:55], v[50:51]
	ds_write2_b32 v44, v48, v49 offset1:1
	v_lshl_add_u64 v[48:49], v[56:57], 0, v[22:23]
	v_mov_b64_e32 v[48:49], v[160:161]
	v_mov_b64_e32 v[50:51], v[162:163]
	s_waitcnt vmcnt(0)
	ds_write2_b32 v47, v48, v49 offset1:1
	v_add_u32_e32 v47, 0x6188, v41
	ds_write2_b32 v47, v50, v51 offset1:1
	v_mov_b64_e32 v[48:49], v[164:165]
	v_mov_b64_e32 v[50:51], v[166:167]
	v_mov_b32_e32 v47, v19
	s_waitcnt vmcnt(0)
	v_pk_mul_f32 v[34:35], v[52:53], v[48:49]
	ds_write2_b32 v36, v34, v35 offset1:1
	v_pk_mul_f32 v[34:35], v[54:55], v[50:51]
	ds_write2_b32 v37, v34, v35 offset1:1
	v_lshl_add_u64 v[34:35], v[56:57], 0, v[28:29]
	v_mov_b64_e32 v[48:49], v[168:169]
	v_mov_b64_e32 v[50:51], v[170:171]
	v_add_u32_e32 v34, 0x71c0, v41
	s_waitcnt vmcnt(0)
	ds_write2_b32 v34, v48, v49 offset1:1
	v_add_u32_e32 v34, 0x71c8, v41
	ds_write2_b32 v34, v50, v51 offset1:1
	v_lshl_add_u64 v[34:35], v[4:5], 0, s[88:89]
	s_waitcnt lgkmcnt(0)
	s_barrier

.LBB0_487:
	s_cmpk_gt_u32 s20, 0x6bf
	s_cbranch_scc0 .LBB0_514
	s_cmpk_gt_u32 s20, 0x7bf
	s_cbranch_scc0 .LBB0_511
	s_cmpk_gt_u32 s20, 0xd3f
	s_cbranch_scc0 .LBB0_508
	s_cmpk_gt_u32 s20, 0xfff
	s_cbranch_scc0 .LBB0_505
	s_cmpk_gt_u32 s20, 0x103f
	v_add_u32_e32 v45, 0x1040, v41
	v_add_u32_e32 v46, 0x1048, v41
	v_add_u32_e32 v43, 0x2080, v41
	v_add_u32_e32 v44, 0x2088, v41
	v_add_u32_e32 v36, 0x30c0, v41
	v_add_u32_e32 v37, 0x30c8, v41
	v_lshlrev_b32_e32 v184, 2, v2
	s_cbranch_scc0 .LBB0_497
	s_add_i32 s0, s20, 0xffffefc0
	s_lshr_b32 s88, s0, 4
	s_lshl_b64 s[26:27], s[88:89], 14
	s_lshl_b32 s28, s88, 6
	s_mov_b32 s29, s89
	v_lshl_add_u64 v[34:35], v[30:31], 0, s[26:27]
	v_lshl_add_u64 v[52:53], s[28:29], 2, v[32:33]
	v_lshl_add_u64 v[48:49], v[8:9], 2, v[34:35]
	global_load_dwordx4 v[48:51], v[48:49], off
	s_nop 0
	global_load_dwordx4 v[52:55], v[52:53], off
	s_lshl_b64 s[0:1], s[28:29], 12
	s_add_u32 s23, s80, s0
	s_addc_u32 s1, s93, s1
	s_lshl_b32 s0, s20, 6
	s_and_b32 s0, s0, 0x3c0
	s_lshl_b32 s30, s0, 2
	s_add_u32 s30, s23, s30
	s_addc_u32 s31, s1, 0
	v_lshl_add_u64 v[56:57], s[30:31], 0, v[184:185]
	v_add_u32_e32 v47, 0x4100, v41
	s_mov_b32 s1, 0
	s_lshl_b32 s88, s88, 7
	s_or_b32 s0, s0, 0xc00
	s_mov_b32 s23, s1
	v_lshl_add_u64 v[172:173], v[56:57], 0, v[10:11]
	global_load_dwordx4 v[144:147], v[172:173], off
	v_lshl_add_u64 v[172:173], v[14:15], 2, v[34:35]
	global_load_dwordx4 v[148:151], v[172:173], off
	v_lshl_add_u64 v[172:173], v[56:57], 0, v[16:17]
	global_load_dwordx4 v[152:155], v[172:173], off
	v_lshl_add_u64 v[172:173], v[20:21], 2, v[34:35]
	global_load_dwordx4 v[156:159], v[172:173], off
	v_lshl_add_u64 v[172:173], v[56:57], 0, v[22:23]
	global_load_dwordx4 v[160:163], v[172:173], off
	v_lshl_add_u64 v[172:173], v[26:27], 2, v[34:35]
	global_load_dwordx4 v[164:167], v[172:173], off
	v_lshl_add_u64 v[172:173], v[56:57], 0, v[28:29]
	global_load_dwordx4 v[168:171], v[172:173], off
	s_waitcnt vmcnt(0)
	v_pk_mul_f32 v[48:49], v[48:49], v[52:53]
	ds_write2_b32 v41, v48, v49 offset1:1
	v_pk_mul_f32 v[48:49], v[50:51], v[54:55]
	ds_write2_b32 v41, v48, v49 offset0:2 offset1:3
	v_lshl_add_u64 v[48:49], v[56:57], 0, v[10:11]
	v_mov_b64_e32 v[48:49], v[144:145]
	v_mov_b64_e32 v[50:51], v[146:147]
	s_waitcnt vmcnt(0)
	ds_write2_b32 v47, v48, v49 offset1:1
	v_add_u32_e32 v47, 0x4108, v41
	v_lshl_add_u64 v[48:49], v[14:15], 2, v[34:35]
	ds_write2_b32 v47, v50, v51 offset1:1
	v_mov_b64_e32 v[48:49], v[148:149]
	v_mov_b64_e32 v[50:51], v[150:151]
	v_add_u32_e32 v47, 0x5140, v41
	s_waitcnt vmcnt(0)
	v_pk_mul_f32 v[48:49], v[52:53], v[48:49]
	ds_write2_b32 v45, v48, v49 offset1:1
	v_pk_mul_f32 v[48:49], v[54:55], v[50:51]
	ds_write2_b32 v46, v48, v49 offset1:1
	v_lshl_add_u64 v[48:49], v[56:57], 0, v[16:17]
	v_mov_b64_e32 v[48:49], v[152:153]
	v_mov_b64_e32 v[50:51], v[154:155]
	s_waitcnt vmcnt(0)
	ds_write2_b32 v47, v48, v49 offset1:1
	v_add_u32_e32 v47, 0x5148, v41
	v_lshl_add_u64 v[48:49], v[20:21], 2, v[34:35]
	ds_write2_b32 v47, v50, v51 offset1:1
	v_mov_b64_e32 v[48:49], v[156:157]
	v_mov_b64_e32 v[50:51], v[158:159]
	v_add_u32_e32 v47, 0x6180, v41
	v_lshl_add_u64 v[34:35], v[26:27], 2, v[34:35]
	s_waitcnt vmcnt(0)
	v_pk_mul_f32 v[48:49], v[52:53], v[48:49]
	ds_write2_b32 v43, v48, v49 offset1:1
	v_pk_mul_f32 v[48:49], v[54:55], v[50:51]
	ds_write2_b32 v44, v48, v49 offset1:1
	v_lshl_add_u64 v[48:49], v[56:57], 0, v[22:23]
	v_mov_b64_e32 v[48:49], v[160:161]
	v_mov_b64_e32 v[50:51], v[162:163]
	s_waitcnt vmcnt(0)
	ds_write2_b32 v47, v48, v49 offset1:1
	v_add_u32_e32 v47, 0x6188, v41
	ds_write2_b32 v47, v50, v51 offset1:1
	v_mov_b64_e32 v[48:49], v[164:165]
	v_mov_b64_e32 v[50:51], v[166:167]
	v_mov_b32_e32 v47, v19
	s_waitcnt vmcnt(0)
	v_pk_mul_f32 v[34:35], v[52:53], v[48:49]
	ds_write2_b32 v36, v34, v35 offset1:1
	v_pk_mul_f32 v[34:35], v[54:55], v[50:51]
	ds_write2_b32 v37, v34, v35 offset1:1
	v_lshl_add_u64 v[34:35], v[56:57], 0, v[28:29]
	v_mov_b64_e32 v[48:49], v[168:169]
	v_mov_b64_e32 v[50:51], v[170:171]
	v_add_u32_e32 v34, 0x71c0, v41
	s_waitcnt vmcnt(0)
	ds_write2_b32 v34, v48, v49 offset1:1
	v_add_u32_e32 v34, 0x71c8, v41
	ds_write2_b32 v34, v50, v51 offset1:1
	v_lshl_add_u64 v[34:35], v[4:5], 0, s[88:89]
	s_waitcnt lgkmcnt(0)
	s_barrier
